# P0b compression phase: one static s_setprio 1 for waves 4-7
# baseline (speedup 1.0000x reference)
.LBB0_10:
	s_load_dword s2, s[0:1], 0xc8
	s_waitcnt lgkmcnt(0)
	s_cmp_gt_i32 s2, 1
	s_cbranch_scc1 .LBB0_188
	s_load_dword s2, s[0:1], 0xcc
	s_waitcnt lgkmcnt(0)
	s_cmp_lt_i32 s2, 2
	s_cbranch_scc1 .LBB0_188
	s_mov_b32 s38, s80
	s_load_dwordx2 s[10:11], s[0:1], 0xc0
	s_waitcnt lgkmcnt(0)
	s_load_dword s39, s[0:1], 0xd4
	s_waitcnt lgkmcnt(0)
	v_mbcnt_lo_u32_b32 v0, -1, 0
	v_mbcnt_hi_u32_b32 v0, -1, v0
	s_cmpk_lt_i32 s38, 0x200
	v_add_u32_e32 v161, s48, v0
	s_load_dwordx2 s[12:13], s[0:1], 40
	s_waitcnt lgkmcnt(0)
	s_load_dwordx2 s[4:5], s[0:1], 16
	s_waitcnt lgkmcnt(0)
	s_load_dwordx2 s[2:3], s[0:1], 56
	s_waitcnt lgkmcnt(0)
	s_load_dwordx2 s[14:15], s[0:1], 0x48
	s_waitcnt lgkmcnt(0)
	s_cbranch_scc0 .LBB0_187
	s_cmp_ge_u32 s33, 4
	s_cbranch_scc0 prio_skip_p0b
	s_setprio 1
prio_skip_p0b:
	v_ashrrev_i32_e32 v4, 2, v161
	v_lshlrev_b32_e32 v0, 12, v161
	v_ashrrev_i32_e32 v5, 31, v4
	v_and_b32_e32 v152, 0x18000, v0
	v_mov_b32_e32 v153, 0
	v_and_b32_e32 v8, 3, v161
	v_lshlrev_b64 v[6:7], 12, v[4:5]
	v_lshl_add_u64 v[154:155], s[4:5], 0, v[152:153]
	v_lshl_add_u64 v[6:7], s[10:11], 0, v[6:7]
	v_lshlrev_b32_e32 v152, 4, v8
	v_lshl_add_u64 v[6:7], v[6:7], 0, v[152:153]
	s_mov_b64 s[4:5], 0x3400000
	v_lshl_add_u64 v[156:157], v[6:7], 0, s[4:5]
	v_lshlrev_b32_e32 v6, 2, v161
	s_movk_i32 s40, 0x50
	v_bfe_u32 v3, v161, 4, 2
	v_ashrrev_i32_e32 v7, 31, v6
	v_mul_lo_u32 v4, v4, s40
	v_lshlrev_b32_e32 v1, 4, v161
	v_lshl_add_u64 v[158:159], v[6:7], 2, s[2:3]
	v_and_b32_e32 v160, 15, v161
	s_add_i32 s2, 0, 0x1f800
	v_lshlrev_b32_e32 v7, 5, v8
	v_add_u32_e32 v9, 0, v4
	v_lshlrev_b32_e32 v4, 4, v3
	v_mov_b32_e32 v5, v153
	v_and_b32_e32 v0, 64, v1
	v_lshlrev_b32_e32 v2, 3, v161
	v_add_u32_e32 v182, s2, v7
	v_add_u32_e32 v162, 0, v4
	v_lshlrev_b32_e32 v6, 8, v160
	v_lshl_add_u64 v[4:5], s[10:11], 0, v[4:5]
	s_mov_b64 s[2:3], 0x3800000
	v_and_b32_e32 v2, 24, v2
	v_lshlrev_b32_e32 v183, 2, v3
	v_lshl_add_u64 v[164:165], v[4:5], 0, s[2:3]
	v_or_b32_e32 v4, 0x1000, v6
	v_or_b32_e32 v8, 0x2000, v6
	v_or_b32_e32 v10, 0x3000, v6
	v_add_u32_e32 v3, 0, v7
	v_lshlrev_b32_e32 v166, 2, v0
	v_add_u32_e32 v0, 0, v1
	v_ashrrev_i32_e32 v163, 5, v161
	s_mov_b32 s17, 0
	s_movk_i32 s41, 0x2000
	v_add_u32_e32 v184, 0x1f880, v3
	v_mov_b32_e32 v185, 0xa00
	v_mov_b32_e32 v167, v153
	v_lshlrev_b32_e32 v168, 2, v2
	v_mov_b32_e32 v169, v153
	v_add_u32_e32 v186, 0x1f800, v0
	s_mov_b64 s[18:19], 0x80000
	s_mov_b32 s42, 0x80000
	v_add_u32_e32 v187, v9, v152
	s_mov_b32 s43, 0x13c00000
	s_movk_i32 s44, 0x7fff
	s_movk_i32 s45, 0x210
	v_lshlrev_b32_e32 v152, 1, v6
	v_lshlrev_b32_e32 v170, 1, v4
	v_lshlrev_b32_e32 v172, 1, v8
	v_lshlrev_b32_e32 v174, 1, v10
	s_mov_b64 s[20:21], 0x80
	s_mov_b64 s[22:23], 0xc0
	s_mov_b64 s[24:25], 0x100
	s_mov_b64 s[26:27], 0x140
	s_mov_b64 s[28:29], 0x180
	s_mov_b64 s[30:31], 0x1c0
	s_mov_b64 s[34:35], 0x2000
	s_mov_b64 s[36:37], 0x2080
	s_branch .LBB0_15

.LBB0_187:
	s_setprio 0
	s_waitcnt lgkmcnt(0)
	s_barrier
